# GEMM unit header: next tile (pm,pn) advanced incrementally from the current one (no integer divisions via v_rcp/readfirstlane), on top of v10
# speedup vs baseline: 1.0052x; 1.0052x over previous
.LBB0_422:
	s_add_i32 s97, s97, 1
	s_mul_i32 s0, s97, s89
	s_mul_hi_u32 s1, s97, s72
	s_add_i32 s1, s1, s0
	s_mul_i32 s0, s97, s72
	s_add_u32 s0, s0, s66
	s_addc_u32 s1, s1, s87
	s_waitcnt lgkmcnt(0)
	v_mov_b64_e32 v[0:1], s[22:23]
	v_cmp_ge_i64_e32 vcc, s[0:1], v[0:1]
	v_cmp_lt_i64_e64 s[4:5], s[0:1], v[0:1]
	s_cbranch_vccnz .LBB0_428
	s_cmpk_lg_u32 s72, 0x100
	s_cbranch_scc1 .Lhdr_orig
	s_and_b32 s1, s55, 3
	s_cmp_lg_u32 s1, 0
	s_cbranch_scc1 .Lhdr_orig
	s_and_b32 s0, s67, 3
	s_lshl_b32 s1, s90, 2
	s_or_b32 s0, s0, s1
	s_add_i32 s0, s0, 32
	s_and_b32 s2, s67, -4
	s_cmp_ge_u32 s0, s64
	s_cselect_b32 s1, s64, 0
	s_cselect_b32 s3, 4, 0
	s_sub_i32 s0, s0, s1
	s_add_i32 s2, s2, s3
	s_cmp_ge_u32 s0, s64
	s_cselect_b32 s1, s64, 0
	s_cselect_b32 s3, 4, 0
	s_sub_i32 s0, s0, s1
	s_add_i32 s2, s2, s3
	s_and_b32 s1, s0, 3
	s_add_i32 s62, s2, s1
	s_lshr_b32 s35, s0, 2
	s_branch .LBB0_428
.Lhdr_orig:
	s_ashr_i32 s1, s0, 31
	s_lshr_b32 s1, s1, 29
	s_add_i32 s2, s0, s1
	s_and_b32 s1, s2, -8
	s_sub_i32 s3, s0, s1
	s_cmp_ge_i32 s3, s86
	s_mov_b64 s[0:1], -1
	s_cbranch_scc0 .LBB0_425
	s_sub_i32 s0, s3, s86
	v_readlane_b32 s1, v255, 28
	s_mul_i32 s0, s0, s1
	v_readlane_b32 s1, v255, 30
	s_mul_i32 s1, s1, s86
	s_add_i32 s16, s0, s1
	s_mov_b64 s[0:1], 0
